# accumulator zeroing at each GEMM unit start: 64 packed ops instead of 128 scalar moves (fewer VALU issue slots per unit), on top of v10
# speedup vs baseline: 1.0206x; 1.0206x over previous
; template <class Epi>
; __device__ __forceinline__ void gemm_phase(LAS unsigned char* lds, const Gemm g, const StaticOrder& S, const Epi& E) {
;     ...
;         for (int a = 0; a < 2; ++a)
; #pragma unroll
;             for (int b = 0; b < 2; ++b)
; #pragma unroll
;                 for (int m = 0; m < 4; ++m)
; #pragma unroll
;                     for (int n = 0; n < 2; ++n) acc[a][b][m][n] = (f32x4){0.f, 0.f, 0.f, 0.f};
;         cur = nxt; cA = nA; cB = nB; ++ui;
.LBB0_108:
	s_ashr_i32 s41, s40, 31
	s_lshl_b64 s[44:45], s[40:41], 20
	s_add_u32 s44, s10, s44
	s_addc_u32 s45, s11, s45
	s_and_b64 s[6:7], s[6:7], exec
	s_cselect_b32 s41, s45, s51
	s_cselect_b32 s62, s44, s50
	s_add_u32 s63, s48, 0x100
	s_addc_u32 s64, s49, 0
	s_add_u32 s65, s50, 0x100
	v_pk_mul_f32 v[0:1], 0, 0
	v_pk_mul_f32 v[2:3], 0, 0
	v_pk_mul_f32 v[4:5], 0, 0
	v_pk_mul_f32 v[6:7], 0, 0
	v_pk_mul_f32 v[8:9], 0, 0
	v_pk_mul_f32 v[10:11], 0, 0
	v_pk_mul_f32 v[12:13], 0, 0
	v_pk_mul_f32 v[14:15], 0, 0
	v_pk_mul_f32 v[16:17], 0, 0
	v_pk_mul_f32 v[18:19], 0, 0
	v_pk_mul_f32 v[20:21], 0, 0
	v_pk_mul_f32 v[22:23], 0, 0
	v_pk_mul_f32 v[24:25], 0, 0
	v_pk_mul_f32 v[26:27], 0, 0
	v_pk_mul_f32 v[28:29], 0, 0
	v_pk_mul_f32 v[30:31], 0, 0
	v_pk_mul_f32 v[32:33], 0, 0
	v_pk_mul_f32 v[34:35], 0, 0
	v_pk_mul_f32 v[36:37], 0, 0
	v_pk_mul_f32 v[38:39], 0, 0
	v_pk_mul_f32 v[40:41], 0, 0
	v_pk_mul_f32 v[42:43], 0, 0
	v_pk_mul_f32 v[44:45], 0, 0
	v_pk_mul_f32 v[46:47], 0, 0
	v_pk_mul_f32 v[48:49], 0, 0
	v_pk_mul_f32 v[50:51], 0, 0
	v_pk_mul_f32 v[52:53], 0, 0
	v_pk_mul_f32 v[54:55], 0, 0
	v_pk_mul_f32 v[56:57], 0, 0
	v_pk_mul_f32 v[58:59], 0, 0
	v_pk_mul_f32 v[60:61], 0, 0
	v_pk_mul_f32 v[62:63], 0, 0
	v_pk_mul_f32 v[64:65], 0, 0
	v_pk_mul_f32 v[66:67], 0, 0
	v_pk_mul_f32 v[68:69], 0, 0
	v_pk_mul_f32 v[70:71], 0, 0
	v_pk_mul_f32 v[72:73], 0, 0
	v_pk_mul_f32 v[74:75], 0, 0
	v_pk_mul_f32 v[76:77], 0, 0
	v_pk_mul_f32 v[78:79], 0, 0
	v_pk_mul_f32 v[80:81], 0, 0
	v_pk_mul_f32 v[82:83], 0, 0
	v_pk_mul_f32 v[84:85], 0, 0
	v_pk_mul_f32 v[86:87], 0, 0
	v_pk_mul_f32 v[88:89], 0, 0
	v_pk_mul_f32 v[90:91], 0, 0
	v_pk_mul_f32 v[92:93], 0, 0
	v_pk_mul_f32 v[94:95], 0, 0
	v_pk_mul_f32 v[96:97], 0, 0
	v_pk_mul_f32 v[98:99], 0, 0
	v_pk_mul_f32 v[100:101], 0, 0
	v_pk_mul_f32 v[102:103], 0, 0
	v_pk_mul_f32 v[104:105], 0, 0
	v_pk_mul_f32 v[106:107], 0, 0
	v_pk_mul_f32 v[108:109], 0, 0
	v_pk_mul_f32 v[110:111], 0, 0
	v_pk_mul_f32 v[112:113], 0, 0
	v_pk_mul_f32 v[114:115], 0, 0
	v_pk_mul_f32 v[116:117], 0, 0
	v_pk_mul_f32 v[118:119], 0, 0
	v_pk_mul_f32 v[120:121], 0, 0
	v_pk_mul_f32 v[122:123], 0, 0
	v_pk_mul_f32 v[124:125], 0, 0
	v_pk_mul_f32 v[126:127], 0, 0
	s_addc_u32 s66, s51, 0
	s_mov_b32 s67, -2

; template <class Epi>
; __device__ __forceinline__ void gemm_phase(LAS unsigned char* lds, const Gemm g, const StaticOrder& S, const Epi& E) {
;     ...
;         for (int a = 0; a < 2; ++a)
; #pragma unroll
;             for (int b = 0; b < 2; ++b)
; #pragma unroll
;                 for (int m = 0; m < 4; ++m)
; #pragma unroll
;                     for (int n = 0; n < 2; ++n) acc[a][b][m][n] = (f32x4){0.f, 0.f, 0.f, 0.f};
;         cur = nxt; cA = nA; cB = nB; ++ui;
.LBB0_229:
	s_add_i32 s34, s81, -2
	s_add_u32 s35, s58, 0x100
	s_addc_u32 s82, s59, 0
	s_add_u32 s83, s60, 0x10000
	v_pk_mul_f32 v[0:1], 0, 0
	v_pk_mul_f32 v[2:3], 0, 0
	v_pk_mul_f32 v[4:5], 0, 0
	v_pk_mul_f32 v[6:7], 0, 0
	v_pk_mul_f32 v[8:9], 0, 0
	v_pk_mul_f32 v[10:11], 0, 0
	v_pk_mul_f32 v[12:13], 0, 0
	v_pk_mul_f32 v[14:15], 0, 0
	v_pk_mul_f32 v[16:17], 0, 0
	v_pk_mul_f32 v[18:19], 0, 0
	v_pk_mul_f32 v[20:21], 0, 0
	v_pk_mul_f32 v[22:23], 0, 0
	v_pk_mul_f32 v[24:25], 0, 0
	v_pk_mul_f32 v[26:27], 0, 0
	v_pk_mul_f32 v[28:29], 0, 0
	v_pk_mul_f32 v[30:31], 0, 0
	v_pk_mul_f32 v[32:33], 0, 0
	v_pk_mul_f32 v[34:35], 0, 0
	v_pk_mul_f32 v[36:37], 0, 0
	v_pk_mul_f32 v[38:39], 0, 0
	v_pk_mul_f32 v[40:41], 0, 0
	v_pk_mul_f32 v[42:43], 0, 0
	v_pk_mul_f32 v[44:45], 0, 0
	v_pk_mul_f32 v[46:47], 0, 0
	v_pk_mul_f32 v[48:49], 0, 0
	v_pk_mul_f32 v[50:51], 0, 0
	v_pk_mul_f32 v[52:53], 0, 0
	v_pk_mul_f32 v[54:55], 0, 0
	v_pk_mul_f32 v[56:57], 0, 0
	v_pk_mul_f32 v[58:59], 0, 0
	v_pk_mul_f32 v[60:61], 0, 0
	v_pk_mul_f32 v[62:63], 0, 0
	v_pk_mul_f32 v[64:65], 0, 0
	v_pk_mul_f32 v[66:67], 0, 0
	v_pk_mul_f32 v[68:69], 0, 0
	v_pk_mul_f32 v[70:71], 0, 0
	v_pk_mul_f32 v[72:73], 0, 0
	v_pk_mul_f32 v[74:75], 0, 0
	v_pk_mul_f32 v[76:77], 0, 0
	v_pk_mul_f32 v[78:79], 0, 0
	v_pk_mul_f32 v[80:81], 0, 0
	v_pk_mul_f32 v[82:83], 0, 0
	v_pk_mul_f32 v[84:85], 0, 0
	v_pk_mul_f32 v[86:87], 0, 0
	v_pk_mul_f32 v[88:89], 0, 0
	v_pk_mul_f32 v[90:91], 0, 0
	v_pk_mul_f32 v[92:93], 0, 0
	v_pk_mul_f32 v[94:95], 0, 0
	v_pk_mul_f32 v[96:97], 0, 0
	v_pk_mul_f32 v[98:99], 0, 0
	v_pk_mul_f32 v[100:101], 0, 0
	v_pk_mul_f32 v[102:103], 0, 0
	v_pk_mul_f32 v[104:105], 0, 0
	v_pk_mul_f32 v[106:107], 0, 0
	v_pk_mul_f32 v[108:109], 0, 0
	v_pk_mul_f32 v[110:111], 0, 0
	v_pk_mul_f32 v[112:113], 0, 0
	v_pk_mul_f32 v[114:115], 0, 0
	v_pk_mul_f32 v[116:117], 0, 0
	v_pk_mul_f32 v[118:119], 0, 0
	v_pk_mul_f32 v[120:121], 0, 0
	v_pk_mul_f32 v[122:123], 0, 0
	v_pk_mul_f32 v[124:125], 0, 0
	v_pk_mul_f32 v[126:127], 0, 0
	s_addc_u32 s84, s61, 0
	s_mov_b32 s58, 0

; template <class Epi>
; __device__ __forceinline__ void gemm_phase(LAS unsigned char* lds, const Gemm g, const StaticOrder& S, const Epi& E) {
;     ...
;         for (int a = 0; a < 2; ++a)
; #pragma unroll
;             for (int b = 0; b < 2; ++b)
; #pragma unroll
;                 for (int m = 0; m < 4; ++m)
; #pragma unroll
;                     for (int n = 0; n < 2; ++n) acc[a][b][m][n] = (f32x4){0.f, 0.f, 0.f, 0.f};
;         cur = nxt; cA = nA; cB = nB; ++ui;
.LBB0_458:
	s_ashr_i32 s87, s86, 31
	s_lshl_b64 s[34:35], s[86:87], 20
	s_add_u32 s90, s16, s34
	s_addc_u32 s91, s17, s35
	s_and_b64 s[12:13], s[12:13], exec
	s_cselect_b32 s18, s91, s97
	s_cselect_b32 s63, s90, s96
	s_add_u32 s87, s94, 0x100
	s_addc_u32 vcc_lo, s95, 0
	s_add_u32 vcc_hi, s96, 0x100
	v_pk_mul_f32 v[0:1], 0, 0
	v_pk_mul_f32 v[2:3], 0, 0
	v_pk_mul_f32 v[4:5], 0, 0
	v_pk_mul_f32 v[6:7], 0, 0
	v_pk_mul_f32 v[8:9], 0, 0
	v_pk_mul_f32 v[10:11], 0, 0
	v_pk_mul_f32 v[12:13], 0, 0
	v_pk_mul_f32 v[14:15], 0, 0
	v_pk_mul_f32 v[16:17], 0, 0
	v_pk_mul_f32 v[18:19], 0, 0
	v_pk_mul_f32 v[20:21], 0, 0
	v_pk_mul_f32 v[22:23], 0, 0
	v_pk_mul_f32 v[24:25], 0, 0
	v_pk_mul_f32 v[26:27], 0, 0
	v_pk_mul_f32 v[28:29], 0, 0
	v_pk_mul_f32 v[30:31], 0, 0
	v_pk_mul_f32 v[32:33], 0, 0
	v_pk_mul_f32 v[34:35], 0, 0
	v_pk_mul_f32 v[36:37], 0, 0
	v_pk_mul_f32 v[38:39], 0, 0
	v_pk_mul_f32 v[40:41], 0, 0
	v_pk_mul_f32 v[42:43], 0, 0
	v_pk_mul_f32 v[44:45], 0, 0
	v_pk_mul_f32 v[46:47], 0, 0
	v_pk_mul_f32 v[48:49], 0, 0
	v_pk_mul_f32 v[50:51], 0, 0
	v_pk_mul_f32 v[52:53], 0, 0
	v_pk_mul_f32 v[54:55], 0, 0
	v_pk_mul_f32 v[56:57], 0, 0
	v_pk_mul_f32 v[58:59], 0, 0
	v_pk_mul_f32 v[60:61], 0, 0
	v_pk_mul_f32 v[62:63], 0, 0
	v_pk_mul_f32 v[64:65], 0, 0
	v_pk_mul_f32 v[66:67], 0, 0
	v_pk_mul_f32 v[68:69], 0, 0
	v_pk_mul_f32 v[70:71], 0, 0
	v_pk_mul_f32 v[72:73], 0, 0
	v_pk_mul_f32 v[74:75], 0, 0
	v_pk_mul_f32 v[76:77], 0, 0
	v_pk_mul_f32 v[78:79], 0, 0
	v_pk_mul_f32 v[80:81], 0, 0
	v_pk_mul_f32 v[82:83], 0, 0
	v_pk_mul_f32 v[84:85], 0, 0
	v_pk_mul_f32 v[86:87], 0, 0
	v_pk_mul_f32 v[88:89], 0, 0
	v_pk_mul_f32 v[90:91], 0, 0
	v_pk_mul_f32 v[92:93], 0, 0
	v_pk_mul_f32 v[94:95], 0, 0
	v_pk_mul_f32 v[96:97], 0, 0
	v_pk_mul_f32 v[98:99], 0, 0
	v_pk_mul_f32 v[100:101], 0, 0
	v_pk_mul_f32 v[102:103], 0, 0
	v_pk_mul_f32 v[104:105], 0, 0
	v_pk_mul_f32 v[106:107], 0, 0
	v_pk_mul_f32 v[108:109], 0, 0
	v_pk_mul_f32 v[110:111], 0, 0
	v_pk_mul_f32 v[112:113], 0, 0
	v_pk_mul_f32 v[114:115], 0, 0
	v_pk_mul_f32 v[116:117], 0, 0
	v_pk_mul_f32 v[118:119], 0, 0
	v_pk_mul_f32 v[120:121], 0, 0
	v_pk_mul_f32 v[122:123], 0, 0
	v_pk_mul_f32 v[124:125], 0, 0
	v_pk_mul_f32 v[126:127], 0, 0
	s_addc_u32 s81, s97, 0
	s_mov_b32 s68, -2

; template <class Epi>
; __device__ __forceinline__ void gemm_phase(LAS unsigned char* lds, const Gemm g, const StaticOrder& S, const Epi& E) {
;     ...
;         for (int a = 0; a < 2; ++a)
; #pragma unroll
;             for (int b = 0; b < 2; ++b)
; #pragma unroll
;                 for (int m = 0; m < 4; ++m)
; #pragma unroll
;                     for (int n = 0; n < 2; ++n) acc[a][b][m][n] = (f32x4){0.f, 0.f, 0.f, 0.f};
;         cur = nxt; cA = nA; cB = nB; ++ui;
.LBB0_901:
	s_add_u32 s47, s56, s36
	v_pk_mul_f32 v[0:1], 0, 0
	v_pk_mul_f32 v[2:3], 0, 0
	v_pk_mul_f32 v[4:5], 0, 0
	v_pk_mul_f32 v[6:7], 0, 0
	v_pk_mul_f32 v[8:9], 0, 0
	v_pk_mul_f32 v[10:11], 0, 0
	v_pk_mul_f32 v[12:13], 0, 0
	v_pk_mul_f32 v[14:15], 0, 0
	v_pk_mul_f32 v[16:17], 0, 0
	v_pk_mul_f32 v[18:19], 0, 0
	v_pk_mul_f32 v[20:21], 0, 0
	v_pk_mul_f32 v[22:23], 0, 0
	v_pk_mul_f32 v[24:25], 0, 0
	v_pk_mul_f32 v[26:27], 0, 0
	v_pk_mul_f32 v[28:29], 0, 0
	v_pk_mul_f32 v[30:31], 0, 0
	v_pk_mul_f32 v[32:33], 0, 0
	v_pk_mul_f32 v[34:35], 0, 0
	v_pk_mul_f32 v[36:37], 0, 0
	v_pk_mul_f32 v[38:39], 0, 0
	v_pk_mul_f32 v[40:41], 0, 0
	v_pk_mul_f32 v[42:43], 0, 0
	v_pk_mul_f32 v[44:45], 0, 0
	v_pk_mul_f32 v[46:47], 0, 0
	v_pk_mul_f32 v[48:49], 0, 0
	v_pk_mul_f32 v[50:51], 0, 0
	v_pk_mul_f32 v[52:53], 0, 0
	v_pk_mul_f32 v[54:55], 0, 0
	v_pk_mul_f32 v[56:57], 0, 0
	v_pk_mul_f32 v[58:59], 0, 0
	v_pk_mul_f32 v[60:61], 0, 0
	v_pk_mul_f32 v[62:63], 0, 0
	v_pk_mul_f32 v[64:65], 0, 0
	v_pk_mul_f32 v[66:67], 0, 0
	v_pk_mul_f32 v[68:69], 0, 0
	v_pk_mul_f32 v[70:71], 0, 0
	v_pk_mul_f32 v[72:73], 0, 0
	v_pk_mul_f32 v[74:75], 0, 0
	v_pk_mul_f32 v[76:77], 0, 0
	v_pk_mul_f32 v[78:79], 0, 0
	v_pk_mul_f32 v[80:81], 0, 0
	v_pk_mul_f32 v[82:83], 0, 0
	v_pk_mul_f32 v[84:85], 0, 0
	v_pk_mul_f32 v[86:87], 0, 0
	v_pk_mul_f32 v[88:89], 0, 0
	v_pk_mul_f32 v[90:91], 0, 0
	v_pk_mul_f32 v[92:93], 0, 0
	v_pk_mul_f32 v[94:95], 0, 0
	v_pk_mul_f32 v[96:97], 0, 0
	v_pk_mul_f32 v[98:99], 0, 0
	v_pk_mul_f32 v[100:101], 0, 0
	v_pk_mul_f32 v[102:103], 0, 0
	v_pk_mul_f32 v[104:105], 0, 0
	v_pk_mul_f32 v[106:107], 0, 0
	v_pk_mul_f32 v[108:109], 0, 0
	v_pk_mul_f32 v[110:111], 0, 0
	v_pk_mul_f32 v[112:113], 0, 0
	v_pk_mul_f32 v[114:115], 0, 0
	v_pk_mul_f32 v[116:117], 0, 0
	v_pk_mul_f32 v[118:119], 0, 0
	v_pk_mul_f32 v[120:121], 0, 0
	v_pk_mul_f32 v[122:123], 0, 0
	v_pk_mul_f32 v[124:125], 0, 0
	v_pk_mul_f32 v[126:127], 0, 0
	s_addc_u32 s49, s57, s37
	s_mov_b32 s64, 0
	s_mov_b64 s[58:59], -1
	s_mov_b64 s[62:63], 0

; template <class Epi>
; __device__ __forceinline__ void gemm_phase(LAS unsigned char* lds, const Gemm g, const StaticOrder& S, const Epi& E) {
;     ...
;         for (int a = 0; a < 2; ++a)
; #pragma unroll
;             for (int b = 0; b < 2; ++b)
; #pragma unroll
;                 for (int m = 0; m < 4; ++m)
; #pragma unroll
;                     for (int n = 0; n < 2; ++n) acc[a][b][m][n] = (f32x4){0.f, 0.f, 0.f, 0.f};
;         cur = nxt; cA = nA; cB = nB; ++ui;
.LBB0_979:
	s_ashr_i32 s15, s14, 31
	s_lshl_b64 s[64:65], s[14:15], 20
	s_add_u32 s15, s20, s64
	s_addc_u32 s64, s21, s65
	s_add_u32 s56, s15, s56
	s_addc_u32 s57, s64, s57
	s_and_b64 s[34:35], s[34:35], exec
	s_cselect_b32 s15, s57, s63
	s_cselect_b32 s79, s56, s62
	s_add_i32 s80, s78, -2
	s_add_u32 s81, s60, 0x100
	s_addc_u32 s82, s61, 0
	s_add_u32 s83, s62, 0x100
	v_pk_mul_f32 v[0:1], 0, 0
	v_pk_mul_f32 v[2:3], 0, 0
	v_pk_mul_f32 v[4:5], 0, 0
	v_pk_mul_f32 v[6:7], 0, 0
	v_pk_mul_f32 v[8:9], 0, 0
	v_pk_mul_f32 v[10:11], 0, 0
	v_pk_mul_f32 v[12:13], 0, 0
	v_pk_mul_f32 v[14:15], 0, 0
	v_pk_mul_f32 v[16:17], 0, 0
	v_pk_mul_f32 v[18:19], 0, 0
	v_pk_mul_f32 v[20:21], 0, 0
	v_pk_mul_f32 v[22:23], 0, 0
	v_pk_mul_f32 v[24:25], 0, 0
	v_pk_mul_f32 v[26:27], 0, 0
	v_pk_mul_f32 v[28:29], 0, 0
	v_pk_mul_f32 v[30:31], 0, 0
	v_pk_mul_f32 v[32:33], 0, 0
	v_pk_mul_f32 v[34:35], 0, 0
	v_pk_mul_f32 v[36:37], 0, 0
	v_pk_mul_f32 v[38:39], 0, 0
	v_pk_mul_f32 v[40:41], 0, 0
	v_pk_mul_f32 v[42:43], 0, 0
	v_pk_mul_f32 v[44:45], 0, 0
	v_pk_mul_f32 v[46:47], 0, 0
	v_pk_mul_f32 v[48:49], 0, 0
	v_pk_mul_f32 v[50:51], 0, 0
	v_pk_mul_f32 v[52:53], 0, 0
	v_pk_mul_f32 v[54:55], 0, 0
	v_pk_mul_f32 v[56:57], 0, 0
	v_pk_mul_f32 v[58:59], 0, 0
	v_pk_mul_f32 v[60:61], 0, 0
	v_pk_mul_f32 v[62:63], 0, 0
	v_pk_mul_f32 v[64:65], 0, 0
	v_pk_mul_f32 v[66:67], 0, 0
	v_pk_mul_f32 v[68:69], 0, 0
	v_pk_mul_f32 v[70:71], 0, 0
	v_pk_mul_f32 v[72:73], 0, 0
	v_pk_mul_f32 v[74:75], 0, 0
	v_pk_mul_f32 v[76:77], 0, 0
	v_pk_mul_f32 v[78:79], 0, 0
	v_pk_mul_f32 v[80:81], 0, 0
	v_pk_mul_f32 v[82:83], 0, 0
	v_pk_mul_f32 v[84:85], 0, 0
	v_pk_mul_f32 v[86:87], 0, 0
	v_pk_mul_f32 v[88:89], 0, 0
	v_pk_mul_f32 v[90:91], 0, 0
	v_pk_mul_f32 v[92:93], 0, 0
	v_pk_mul_f32 v[94:95], 0, 0
	v_pk_mul_f32 v[96:97], 0, 0
	v_pk_mul_f32 v[98:99], 0, 0
	v_pk_mul_f32 v[100:101], 0, 0
	v_pk_mul_f32 v[102:103], 0, 0
	v_pk_mul_f32 v[104:105], 0, 0
	v_pk_mul_f32 v[106:107], 0, 0
	v_pk_mul_f32 v[108:109], 0, 0
	v_pk_mul_f32 v[110:111], 0, 0
	v_pk_mul_f32 v[112:113], 0, 0
	v_pk_mul_f32 v[114:115], 0, 0
	v_pk_mul_f32 v[116:117], 0, 0
	v_pk_mul_f32 v[118:119], 0, 0
	v_pk_mul_f32 v[120:121], 0, 0
	v_pk_mul_f32 v[122:123], 0, 0
	v_pk_mul_f32 v[124:125], 0, 0
	v_pk_mul_f32 v[126:127], 0, 0
	s_addc_u32 s84, s63, 0
	s_mov_b32 s34, 0

; template <class Epi>
; __device__ __forceinline__ void gemm_phase(LAS unsigned char* lds, const Gemm g, const StaticOrder& S, const Epi& E) {
;     ...
;         for (int a = 0; a < 2; ++a)
; #pragma unroll
;             for (int b = 0; b < 2; ++b)
; #pragma unroll
;                 for (int m = 0; m < 4; ++m)
; #pragma unroll
;                     for (int n = 0; n < 2; ++n) acc[a][b][m][n] = (f32x4){0.f, 0.f, 0.f, 0.f};
;         cur = nxt; cA = nA; cB = nB; ++ui;
.LBB0_1206:
	s_ashr_i32 s45, s44, 31
	s_lshl_b64 s[48:49], s[44:45], 20
	s_add_u32 s48, s12, s48
	s_addc_u32 s49, s13, s49
	s_and_b64 s[10:11], s[10:11], exec
	s_cselect_b32 s45, s49, s55
	s_cselect_b32 s64, s48, s54
	s_add_u32 s65, s52, 0x100
	s_addc_u32 s66, s53, 0
	s_add_u32 s67, s54, 0x100
	v_pk_mul_f32 v[0:1], 0, 0
	v_pk_mul_f32 v[2:3], 0, 0
	v_pk_mul_f32 v[4:5], 0, 0
	v_pk_mul_f32 v[6:7], 0, 0
	v_pk_mul_f32 v[8:9], 0, 0
	v_pk_mul_f32 v[10:11], 0, 0
	v_pk_mul_f32 v[12:13], 0, 0
	v_pk_mul_f32 v[14:15], 0, 0
	v_pk_mul_f32 v[16:17], 0, 0
	v_pk_mul_f32 v[18:19], 0, 0
	v_pk_mul_f32 v[20:21], 0, 0
	v_pk_mul_f32 v[22:23], 0, 0
	v_pk_mul_f32 v[24:25], 0, 0
	v_pk_mul_f32 v[26:27], 0, 0
	v_pk_mul_f32 v[28:29], 0, 0
	v_pk_mul_f32 v[30:31], 0, 0
	v_pk_mul_f32 v[32:33], 0, 0
	v_pk_mul_f32 v[34:35], 0, 0
	v_pk_mul_f32 v[36:37], 0, 0
	v_pk_mul_f32 v[38:39], 0, 0
	v_pk_mul_f32 v[40:41], 0, 0
	v_pk_mul_f32 v[42:43], 0, 0
	v_pk_mul_f32 v[44:45], 0, 0
	v_pk_mul_f32 v[46:47], 0, 0
	v_pk_mul_f32 v[48:49], 0, 0
	v_pk_mul_f32 v[50:51], 0, 0
	v_pk_mul_f32 v[52:53], 0, 0
	v_pk_mul_f32 v[54:55], 0, 0
	v_pk_mul_f32 v[56:57], 0, 0
	v_pk_mul_f32 v[58:59], 0, 0
	v_pk_mul_f32 v[60:61], 0, 0
	v_pk_mul_f32 v[62:63], 0, 0
	v_pk_mul_f32 v[64:65], 0, 0
	v_pk_mul_f32 v[66:67], 0, 0
	v_pk_mul_f32 v[68:69], 0, 0
	v_pk_mul_f32 v[70:71], 0, 0
	v_pk_mul_f32 v[72:73], 0, 0
	v_pk_mul_f32 v[74:75], 0, 0
	v_pk_mul_f32 v[76:77], 0, 0
	v_pk_mul_f32 v[78:79], 0, 0
	v_pk_mul_f32 v[80:81], 0, 0
	v_pk_mul_f32 v[82:83], 0, 0
	v_pk_mul_f32 v[84:85], 0, 0
	v_pk_mul_f32 v[86:87], 0, 0
	v_pk_mul_f32 v[88:89], 0, 0
	v_pk_mul_f32 v[90:91], 0, 0
	v_pk_mul_f32 v[92:93], 0, 0
	v_pk_mul_f32 v[94:95], 0, 0
	v_pk_mul_f32 v[96:97], 0, 0
	v_pk_mul_f32 v[98:99], 0, 0
	v_pk_mul_f32 v[100:101], 0, 0
	v_pk_mul_f32 v[102:103], 0, 0
	v_pk_mul_f32 v[104:105], 0, 0
	v_pk_mul_f32 v[106:107], 0, 0
	v_pk_mul_f32 v[108:109], 0, 0
	v_pk_mul_f32 v[110:111], 0, 0
	v_pk_mul_f32 v[112:113], 0, 0
	v_pk_mul_f32 v[114:115], 0, 0
	v_pk_mul_f32 v[116:117], 0, 0
	v_pk_mul_f32 v[118:119], 0, 0
	v_pk_mul_f32 v[120:121], 0, 0
	v_pk_mul_f32 v[122:123], 0, 0
	v_pk_mul_f32 v[124:125], 0, 0
	v_pk_mul_f32 v[126:127], 0, 0
	s_addc_u32 s68, s55, 0
	s_mov_b32 s69, -2

; template <class Epi>
; __device__ __forceinline__ void gemm_phase(LAS unsigned char* lds, const Gemm g, const StaticOrder& S, const Epi& E) {
;     ...
;         for (int a = 0; a < 2; ++a)
; #pragma unroll
;             for (int b = 0; b < 2; ++b)
; #pragma unroll
;                 for (int m = 0; m < 4; ++m)
; #pragma unroll
;                     for (int n = 0; n < 2; ++n) acc[a][b][m][n] = (f32x4){0.f, 0.f, 0.f, 0.f};
;         cur = nxt; cA = nA; cB = nB; ++ui;
.LBB0_1286:
	s_add_i32 s84, s83, -2
	s_add_u32 s85, s48, 0x100
	s_addc_u32 s86, s49, 0
	s_add_u32 s87, s50, 0x10000
	v_pk_mul_f32 v[0:1], 0, 0
	v_pk_mul_f32 v[2:3], 0, 0
	v_pk_mul_f32 v[4:5], 0, 0
	v_pk_mul_f32 v[6:7], 0, 0
	v_pk_mul_f32 v[8:9], 0, 0
	v_pk_mul_f32 v[10:11], 0, 0
	v_pk_mul_f32 v[12:13], 0, 0
	v_pk_mul_f32 v[14:15], 0, 0
	v_pk_mul_f32 v[16:17], 0, 0
	v_pk_mul_f32 v[18:19], 0, 0
	v_pk_mul_f32 v[20:21], 0, 0
	v_pk_mul_f32 v[22:23], 0, 0
	v_pk_mul_f32 v[24:25], 0, 0
	v_pk_mul_f32 v[26:27], 0, 0
	v_pk_mul_f32 v[28:29], 0, 0
	v_pk_mul_f32 v[30:31], 0, 0
	v_pk_mul_f32 v[32:33], 0, 0
	v_pk_mul_f32 v[34:35], 0, 0
	v_pk_mul_f32 v[36:37], 0, 0
	v_pk_mul_f32 v[38:39], 0, 0
	v_pk_mul_f32 v[40:41], 0, 0
	v_pk_mul_f32 v[42:43], 0, 0
	v_pk_mul_f32 v[44:45], 0, 0
	v_pk_mul_f32 v[46:47], 0, 0
	v_pk_mul_f32 v[48:49], 0, 0
	v_pk_mul_f32 v[50:51], 0, 0
	v_pk_mul_f32 v[52:53], 0, 0
	v_pk_mul_f32 v[54:55], 0, 0
	v_pk_mul_f32 v[56:57], 0, 0
	v_pk_mul_f32 v[58:59], 0, 0
	v_pk_mul_f32 v[60:61], 0, 0
	v_pk_mul_f32 v[62:63], 0, 0
	v_pk_mul_f32 v[64:65], 0, 0
	v_pk_mul_f32 v[66:67], 0, 0
	v_pk_mul_f32 v[68:69], 0, 0
	v_pk_mul_f32 v[70:71], 0, 0
	v_pk_mul_f32 v[72:73], 0, 0
	v_pk_mul_f32 v[74:75], 0, 0
	v_pk_mul_f32 v[76:77], 0, 0
	v_pk_mul_f32 v[78:79], 0, 0
	v_pk_mul_f32 v[80:81], 0, 0
	v_pk_mul_f32 v[82:83], 0, 0
	v_pk_mul_f32 v[84:85], 0, 0
	v_pk_mul_f32 v[86:87], 0, 0
	v_pk_mul_f32 v[88:89], 0, 0
	v_pk_mul_f32 v[90:91], 0, 0
	v_pk_mul_f32 v[92:93], 0, 0
	v_pk_mul_f32 v[94:95], 0, 0
	v_pk_mul_f32 v[96:97], 0, 0
	v_pk_mul_f32 v[98:99], 0, 0
	v_pk_mul_f32 v[100:101], 0, 0
	v_pk_mul_f32 v[102:103], 0, 0
	v_pk_mul_f32 v[104:105], 0, 0
	v_pk_mul_f32 v[106:107], 0, 0
	v_pk_mul_f32 v[108:109], 0, 0
	v_pk_mul_f32 v[110:111], 0, 0
	v_pk_mul_f32 v[112:113], 0, 0
	v_pk_mul_f32 v[114:115], 0, 0
	v_pk_mul_f32 v[116:117], 0, 0
	v_pk_mul_f32 v[118:119], 0, 0
	v_pk_mul_f32 v[120:121], 0, 0
	v_pk_mul_f32 v[122:123], 0, 0
	v_pk_mul_f32 v[124:125], 0, 0
	v_pk_mul_f32 v[126:127], 0, 0
	s_addc_u32 s88, s51, 0
	s_mov_b32 s48, 0
